# P2 short-conv loop: butterfly sum steps xor 1/2/4/8 as DPP adds (quad_perm, row_half_mirror, row_mirror) instead of ds_swizzle LDS round trips waited on at once
# speedup vs baseline: 1.0045x; 1.0045x over previous
.LBB0_270:
	v_or_b32_e32 v124, s8, v164
	v_med3_i32 v26, v124, 0, v197
	v_max_i32_e32 v27, -4, v124
	v_ashrrev_i32_e32 v125, 31, v124
	v_mov_b64_e32 v[24:25], s[72:73]
	v_or_b32_e32 v30, s38, v26
	v_add_u32_e32 v34, 4, v27
	v_lshl_add_u64 v[26:27], s[38:39], 0, v[124:125]
	v_add_u32_e32 v28, -1, v124
	v_or_b32_e32 v128, 1, v124
	v_mad_u64_u32 v[24:25], s[10:11], v26, s28, v[24:25]
	v_or_b32_e32 v126, 2, v124
	v_or_b32_e32 v122, 3, v124
	v_med3_i32 v29, v28, 0, v197
	v_med3_i32 v31, v128, 0, v197
	v_min_u32_e32 v40, 0xfff, v34
	v_mad_i32_i24 v25, v27, s28, v25
	v_med3_i32 v32, v126, 0, v197
	v_med3_i32 v33, v122, 0, v197
	v_cmp_gt_u32_e32 vcc, s46, v28
	v_or_b32_e32 v35, s38, v29
	v_mad_u64_u32 v[28:29], s[10:11], v30, s28, v[70:71]
	v_or_b32_e32 v36, s38, v31
	v_lshlrev_b64 v[30:31], 11, v[26:27]
	v_or_b32_e32 v26, s38, v40
	v_lshl_add_u64 v[24:25], v[24:25], 0, v[178:179]
	v_cndmask_b32_e64 v64, 0, 1.0, vcc
	v_or_b32_e32 v37, s38, v32
	v_or_b32_e32 v38, s38, v33
	v_lshl_add_u64 v[146:147], v[72:73], 0, v[30:31]
	v_mad_u64_u32 v[30:31], s[10:11], v26, s28, v[70:71]
	v_add_co_u32_e32 v26, vcc, s46, v24
	v_mad_u64_u32 v[32:33], s[10:11], v35, s28, v[70:71]
	v_mad_i32_i24 v29, s39, v187, v29
	v_mad_u64_u32 v[34:35], s[10:11], v36, s28, v[70:71]
	v_mad_u64_u32 v[36:37], s[10:11], v37, s28, v[70:71]
	v_mad_u64_u32 v[38:39], s[10:11], v38, s28, v[70:71]
	v_addc_co_u32_e32 v27, vcc, 0, v25, vcc
	global_load_dwordx4 v[130:133], v[28:29], off offset:2560
	v_mad_i32_i24 v33, s39, v187, v33
	v_mad_i32_i24 v35, s39, v187, v35
	v_mad_i32_i24 v37, s39, v187, v37
	v_mad_i32_i24 v39, s39, v187, v39
	global_load_dwordx4 v[134:137], v[28:29], off offset:3584
	global_load_dwordx4 v[138:141], v[34:35], off offset:2560
	global_load_dwordx4 v[142:145], v[32:33], off offset:2560
	global_load_dwordx4 v[148:151], v[34:35], off offset:3584
	global_load_dwordx4 v[152:155], v[32:33], off offset:3584
	global_load_dwordx4 v[156:159], v[36:37], off offset:3584
	global_load_dwordx4 v[160:163], v[36:37], off offset:2560
	global_load_dwordx4 v[48:51], v[38:39], off offset:3584
	global_load_dwordx4 v[166:169], v[24:25], off offset:1536
	v_add_co_u32_e32 v28, vcc, s54, v24
	v_mad_i32_i24 v31, s39, v187, v31
	s_nop 0
	v_addc_co_u32_e32 v29, vcc, 0, v25, vcc
	v_add_co_u32_e32 v36, vcc, s55, v24
	s_mov_b32 s8, 4
	s_nop 0
	v_addc_co_u32_e32 v37, vcc, 0, v25, vcc
	v_add_co_u32_e32 v174, vcc, s64, v24
	s_waitcnt vmcnt(8)
	v_lshlrev_b32_e32 v200, 16, v135
	v_addc_co_u32_e32 v175, vcc, 0, v25, vcc
	v_add_co_u32_e32 v180, vcc, s65, v24
	s_waitcnt vmcnt(7)
	v_lshlrev_b32_e32 v211, 16, v138
	v_addc_co_u32_e32 v181, vcc, 0, v25, vcc
	global_load_dwordx4 v[52:55], v[38:39], off offset:2560
	global_load_dwordx4 v[32:35], v[30:31], off offset:3584
	global_load_dwordx4 v[170:173], v[26:27], off offset:1536
	global_load_dwordx4 v[56:59], v[28:29], off offset:-4096
	global_load_dwordx4 v[60:63], v[28:29], off
	global_load_dwordx4 v[40:43], v[28:29], off offset:2560
	global_load_dwordx4 v[44:47], v[36:37], off offset:2560
	s_nop 0
	global_load_dwordx4 v[24:27], v[174:175], off offset:1024
	global_load_dwordx4 v[36:39], v[30:31], off offset:2560
	s_nop 0
	global_load_dwordx4 v[28:31], v[180:181], off offset:1024
	s_waitcnt vmcnt(16)
	v_lshlrev_b32_e32 v210, 16, v142
	s_waitcnt vmcnt(15)
	v_lshlrev_b32_e32 v213, 16, v148
	s_waitcnt vmcnt(14)
	v_lshlrev_b32_e32 v212, 16, v152
	v_and_b32_e32 v215, 0xffff0000, v138
	v_and_b32_e32 v214, 0xffff0000, v142
	v_and_b32_e32 v217, 0xffff0000, v148
	v_and_b32_e32 v216, 0xffff0000, v152
	v_lshlrev_b32_e32 v219, 16, v139
	v_lshlrev_b32_e32 v218, 16, v143
	v_lshlrev_b32_e32 v221, 16, v149
	v_lshlrev_b32_e32 v220, 16, v153
	v_and_b32_e32 v139, 0xffff0000, v139
	v_and_b32_e32 v138, 0xffff0000, v143
	v_and_b32_e32 v143, 0xffff0000, v149
	v_and_b32_e32 v142, 0xffff0000, v153
	v_lshlrev_b32_e32 v149, 16, v140
	v_lshlrev_b32_e32 v148, 16, v144
	v_lshlrev_b32_e32 v153, 16, v150
	v_lshlrev_b32_e32 v152, 16, v154
	v_and_b32_e32 v223, 0xffff0000, v140
	v_and_b32_e32 v222, 0xffff0000, v144
	v_and_b32_e32 v225, 0xffff0000, v150
	v_and_b32_e32 v224, 0xffff0000, v154
	v_lshlrev_b32_e32 v227, 16, v141
	v_lshlrev_b32_e32 v226, 16, v145
	v_lshlrev_b32_e32 v229, 16, v151
	v_lshlrev_b32_e32 v228, 16, v155
	v_and_b32_e32 v141, 0xffff0000, v141
	v_and_b32_e32 v140, 0xffff0000, v145
	v_and_b32_e32 v145, 0xffff0000, v151
	v_and_b32_e32 v144, 0xffff0000, v155
	v_and_b32_e32 v202, 0xffff0000, v135
	s_waitcnt vmcnt(13)
	v_lshlrev_b32_e32 v193, 16, v156
	v_and_b32_e32 v135, 0xffff0000, v156
	v_lshlrev_b32_e32 v201, 16, v157
	v_and_b32_e32 v203, 0xffff0000, v157
	v_pk_mul_f32 v[150:151], v[210:211], v[212:213]
	v_pk_mul_f32 v[154:155], v[214:215], v[216:217]
	v_pk_mul_f32 v[156:157], v[218:219], v[220:221]
	v_pk_mul_f32 v[138:139], v[138:139], v[142:143]
	v_pk_mul_f32 v[142:143], v[148:149], v[152:153]
	v_pk_mul_f32 v[148:149], v[222:223], v[224:225]
	v_pk_mul_f32 v[210:211], v[226:227], v[228:229]
	v_pk_mul_f32 v[140:141], v[140:141], v[144:145]
	v_lshlrev_b32_e32 v180, 16, v131
	v_and_b32_e32 v182, 0xffff0000, v131
	v_lshlrev_b32_e32 v188, 16, v133
	v_and_b32_e32 v190, 0xffff0000, v133
	v_lshlrev_b32_e32 v206, 16, v137
	v_and_b32_e32 v208, 0xffff0000, v137
	s_waitcnt vmcnt(12)
	v_lshlrev_b32_e32 v175, 16, v160
	v_and_b32_e32 v131, 0xffff0000, v160
	v_lshlrev_b32_e32 v181, 16, v161
	v_and_b32_e32 v183, 0xffff0000, v161
	v_lshlrev_b32_e32 v185, 16, v162
	v_lshlrev_b32_e32 v205, 16, v158
	v_and_b32_e32 v133, 0xffff0000, v162
	v_and_b32_e32 v137, 0xffff0000, v158
	v_lshlrev_b32_e32 v189, 16, v163
	v_lshlrev_b32_e32 v207, 16, v159
	v_and_b32_e32 v191, 0xffff0000, v163
	v_and_b32_e32 v209, 0xffff0000, v159
	v_pk_mul_f32 v[162:163], v[64:65], v[150:151]
	v_pk_mul_f32 v[160:161], v[64:65], v[154:155]
	v_pk_mul_f32 v[158:159], v[64:65], v[156:157]
	v_pk_mul_f32 v[156:157], v[64:65], v[138:139]
	v_pk_mul_f32 v[154:155], v[64:65], v[142:143]
	v_pk_mul_f32 v[152:153], v[64:65], v[148:149]
	v_pk_mul_f32 v[150:151], v[64:65], v[210:211]
	v_pk_mul_f32 v[148:149], v[64:65], v[140:141]
	v_lshlrev_b32_e32 v174, 16, v130
	v_and_b32_e32 v130, 0xffff0000, v130
	s_waitcnt vmcnt(7)
	v_lshlrev_b32_e32 v230, 16, v170
	v_and_b32_e32 v232, 0xffff0000, v170
	v_mul_f32_e32 v64, 0xbfb8aa3b, v230
	v_lshlrev_b32_e32 v234, 16, v171
	v_mul_f32_e32 v67, 0xbfb8aa3b, v232
	v_exp_f32_e32 v64, v64
	v_lshlrev_b32_e32 v192, 16, v134
	v_and_b32_e32 v134, 0xffff0000, v134
	v_lshlrev_b32_e32 v231, 16, v166
	v_and_b32_e32 v233, 0xffff0000, v166
	v_and_b32_e32 v166, 0xffff0000, v171
	v_mul_f32_e32 v123, 0xbfb8aa3b, v234
	v_exp_f32_e32 v67, v67
	v_lshlrev_b32_e32 v236, 16, v172
	v_pk_mul_f32 v[144:145], v[192:193], v[174:175]
	v_pk_mul_f32 v[130:131], v[134:135], v[130:131]
	v_pk_mul_f32 v[134:135], v[200:201], v[180:181]
	v_pk_mul_f32 v[170:171], v[202:203], v[182:183]
	v_pk_mul_f32 v[180:181], v[208:209], v[190:191]
	v_mul_f32_e32 v125, 0xbfb8aa3b, v166
	v_exp_f32_e32 v123, v123
	v_lshlrev_b32_e32 v184, 16, v132
	v_lshlrev_b32_e32 v204, 16, v136
	v_and_b32_e32 v238, 0xffff0000, v172
	v_mul_f32_e32 v127, 0xbfb8aa3b, v236
	v_pk_mul_f32 v[144:145], v[68:69], v[144:145]
	v_pk_mul_f32 v[142:143], v[68:69], v[130:131]
	v_pk_mul_f32 v[138:139], v[68:69], v[170:171]
	v_pk_mul_f32 v[130:131], v[68:69], v[180:181]
	v_pk_mul_f32 v[170:171], v[86:87], v[162:163]
	v_pk_mul_f32 v[190:191], v[76:77], v[148:149]
	v_exp_f32_e32 v125, v125
	v_and_b32_e32 v132, 0xffff0000, v132
	v_and_b32_e32 v136, 0xffff0000, v136
	v_lshlrev_b32_e32 v237, 16, v168
	v_and_b32_e32 v239, 0xffff0000, v168
	v_lshlrev_b32_e32 v240, 16, v173
	v_and_b32_e32 v168, 0xffff0000, v173
	v_pk_mul_f32 v[172:173], v[204:205], v[184:185]
	v_mul_f32_e32 v129, 0xbfb8aa3b, v238
	v_exp_f32_e32 v127, v127
	v_pk_mul_f32 v[192:193], v[86:87], v[144:145]
	v_fma_f32 v144, v20, v144, v170
	v_fma_f32 v170, v19, v130, v190
	v_add_f32_e32 v64, 1.0, v64
	v_pk_mul_f32 v[132:133], v[136:137], v[132:133]
	v_pk_mul_f32 v[174:175], v[206:207], v[188:189]
	v_mul_f32_e32 v165, 0xbfb8aa3b, v240
	v_pk_mul_f32 v[136:137], v[68:69], v[172:173]
	v_pk_mul_f32 v[172:173], v[88:89], v[160:161]
	v_exp_f32_e32 v129, v129
	v_add_f32_e32 v191, v170, v191
	v_add_f32_e32 v67, 1.0, v67
	v_rcp_f32_e32 v170, v64
	v_mul_f32_e32 v186, 0xbfb8aa3b, v168
	v_pk_mul_f32 v[140:141], v[68:69], v[134:135]
	v_pk_mul_f32 v[134:135], v[68:69], v[132:133]
	v_pk_mul_f32 v[132:133], v[68:69], v[174:175]
	v_pk_mul_f32 v[174:175], v[82:83], v[158:159]
	v_exp_f32_e32 v148, v165
	v_pk_mul_f32 v[200:201], v[88:89], v[142:143]
	v_fma_f32 v142, v21, v142, v172
	v_add_f32_e32 v123, 1.0, v123
	v_rcp_f32_e32 v172, v67
	v_pk_mul_f32 v[180:181], v[84:85], v[156:157]
	v_pk_mul_f32 v[188:189], v[74:75], v[150:151]
	v_exp_f32_e32 v150, v186
	v_pk_mul_f32 v[202:203], v[82:83], v[140:141]
	v_fma_f32 v140, v22, v140, v174
	v_add_f32_e32 v125, 1.0, v125
	v_rcp_f32_e32 v174, v123
	v_pk_mul_f32 v[182:183], v[78:79], v[154:155]
	v_pk_mul_f32 v[204:205], v[84:85], v[138:139]
	v_fma_f32 v138, v23, v138, v180
	v_add_f32_e32 v171, v144, v171
	v_add_f32_e32 v127, 1.0, v127
	v_rcp_f32_e32 v180, v125
	v_pk_mul_f32 v[184:185], v[80:81], v[152:153]
	v_pk_mul_f32 v[206:207], v[78:79], v[136:137]
	v_pk_mul_f32 v[210:211], v[74:75], v[132:133]
	v_fma_f32 v136, v16, v136, v182
	v_fma_f32 v132, v18, v132, v188
	v_add_f32_e32 v173, v142, v173
	v_add_f32_e32 v129, 1.0, v129
	v_rcp_f32_e32 v182, v127
	v_pk_mul_f32 v[170:171], v[170:171], v[230:231]
	v_lshlrev_b32_e32 v235, 16, v167
	v_pk_mul_f32 v[208:209], v[80:81], v[134:135]
	v_fma_f32 v134, v17, v134, v184
	v_add_f32_e32 v175, v140, v175
	v_add_f32_e32 v189, v132, v189
	v_add_f32_e32 v132, 1.0, v148
	v_rcp_f32_e32 v184, v129
	v_pk_mul_f32 v[172:173], v[172:173], v[232:233]
	v_mul_f32_e32 v64, v171, v171
	v_and_b32_e32 v167, 0xffff0000, v167
	v_add_f32_e32 v181, v138, v181
	v_add_f32_e32 v185, v134, v185
	v_add_f32_e32 v134, 1.0, v150
	v_rcp_f32_e32 v188, v132
	v_pk_mul_f32 v[174:175], v[174:175], v[234:235]
	v_fmac_f32_e32 v64, v173, v173
	v_add_f32_e32 v183, v136, v183
	v_rcp_f32_e32 v190, v134
	v_pk_mul_f32 v[166:167], v[180:181], v[166:167]
	v_fmac_f32_e32 v64, v175, v175
	v_pk_mul_f32 v[180:181], v[182:183], v[236:237]
	v_fmac_f32_e32 v64, v167, v167
	v_lshlrev_b32_e32 v241, 16, v169
	v_pk_mul_f32 v[182:183], v[184:185], v[238:239]
	v_fmac_f32_e32 v64, v181, v181
	v_and_b32_e32 v169, 0xffff0000, v169
	v_pk_mul_f32 v[184:185], v[188:189], v[240:241]
	v_fmac_f32_e32 v64, v183, v183
	v_pk_mul_f32 v[168:169], v[190:191], v[168:169]
	v_fmac_f32_e32 v64, v185, v185
	v_fmac_f32_e32 v64, v169, v169
	v_fma_f32 v152, v20, v163, v192
	v_fma_f32 v154, v21, v161, v200
	v_fma_f32 v156, v22, v159, v202
	v_fma_f32 v158, v23, v157, v204
	v_add_f32_dpp v64, v64, v64 quad_perm:[1,0,3,2] row_mask:0xf bank_mask:0xf
	v_fma_f32 v160, v16, v155, v206
	v_fma_f32 v162, v17, v153, v208
	v_fma_f32 v165, v18, v151, v210
	v_add_f32_e32 v193, v152, v193
	v_add_f32_dpp v64, v64, v64 quad_perm:[2,3,0,1] row_mask:0xf bank_mask:0xf
	v_add_f32_e32 v201, v154, v201
	v_add_f32_e32 v203, v156, v203
	v_add_f32_e32 v205, v158, v205
	v_add_f32_e32 v207, v160, v207
	v_add_f32_dpp v64, v64, v64 row_half_mirror row_mask:0xf bank_mask:0xf
	v_add_f32_e32 v209, v162, v209
	v_add_f32_e32 v211, v165, v211
	v_add_f32_dpp v64, v64, v64 row_mirror row_mask:0xf bank_mask:0xf
	ds_swizzle_b32 v67, v64 offset:swizzle(SWAP,16)
	s_waitcnt lgkmcnt(0)
	v_add_f32_e32 v64, v64, v67
	v_mov_b32_e32 v67, v64
	s_nop 1
	v_permlane32_swap_b32_e32 v64, v67
	v_add_f32_e32 v64, v64, v67
	v_fmamk_f32 v64, v64, 0x3b000000, v196
	v_mul_f32_e32 v67, 0x4b800000, v64
	v_cmp_gt_f32_e32 vcc, s35, v64
	s_nop 1
	v_cndmask_b32_e32 v64, v64, v67, vcc
	v_rsq_f32_e32 v64, v64
	s_nop 0
	v_mul_f32_e32 v67, 0x45800000, v64
	v_cndmask_b32_e32 v64, v64, v67, vcc
	v_mul_f32_e32 v67, v171, v64
	v_mul_f32_e32 v123, v173, v64
	v_mul_f32_e32 v125, v175, v64
	v_mul_f32_e32 v127, v167, v64
	v_mul_f32_e32 v129, v181, v64
	v_mul_f32_e32 v132, v183, v64
	v_mul_f32_e32 v134, v185, v64
	v_mul_f32_e32 v64, v169, v64
	v_mul_f32_e32 v67, v170, v67
	v_mul_f32_e32 v123, v172, v123
	v_mul_f32_e32 v125, v174, v125
	v_mul_f32_e32 v127, v166, v127
	v_mul_f32_e32 v129, v180, v129
	v_mul_f32_e32 v132, v182, v132
	v_mul_f32_e32 v134, v184, v134
	v_mul_f32_e32 v64, v168, v64
	v_cvt_pk_bf16_f32 v166, v67, v123
	v_cvt_pk_bf16_f32 v167, v125, v127
	v_cvt_pk_bf16_f32 v168, v129, v132
	v_cvt_pk_bf16_f32 v169, v134, v64
	global_store_dwordx4 v[146:147], v[166:169], off offset:1024
	v_pk_mul_f32 v[146:147], v[76:77], v[130:131]
	s_waitcnt vmcnt(6)
	v_and_b32_e32 v166, 0xffff0000, v60
	v_fma_f32 v64, v19, v149, v146
	v_lshlrev_b32_e32 v146, 16, v60
	v_mul_f32_e32 v60, 0xbfb8aa3b, v166
	v_exp_f32_e32 v60, v60
	v_mul_f32_e32 v67, 0xbfb8aa3b, v146
	v_exp_f32_e32 v67, v67
	v_add_f32_e32 v169, v64, v147
	v_add_f32_e32 v60, 1.0, v60
	v_rcp_f32_e32 v200, v60
	v_lshlrev_b32_e32 v60, 16, v61
	v_add_f32_e32 v64, 1.0, v67
	v_lshlrev_b32_e32 v147, 16, v56
	v_and_b32_e32 v167, 0xffff0000, v56
	v_mul_f32_e32 v56, 0xbfb8aa3b, v60
	v_rcp_f32_e32 v192, v64
	v_exp_f32_e32 v64, v56
	v_and_b32_e32 v56, 0xffff0000, v61
	v_mul_f32_e32 v61, 0xbfb8aa3b, v56
	v_exp_f32_e32 v67, v61
	v_add_f32_e32 v64, 1.0, v64
	v_rcp_f32_e32 v202, v64
	v_lshlrev_b32_e32 v170, 16, v62
	v_add_f32_e32 v64, 1.0, v67
	v_rcp_f32_e32 v204, v64
	v_mul_f32_e32 v64, 0xbfb8aa3b, v170
	v_exp_f32_e32 v64, v64
	v_lshlrev_b32_e32 v61, 16, v57
	v_and_b32_e32 v57, 0xffff0000, v57
	v_pk_mul_f32 v[172:173], v[204:205], v[56:57]
	v_add_f32_e32 v56, 1.0, v64
	v_rcp_f32_e32 v206, v56
	v_and_b32_e32 v56, 0xffff0000, v62
	v_mul_f32_e32 v57, 0xbfb8aa3b, v56
	v_exp_f32_e32 v62, v57
	v_lshlrev_b32_e32 v171, 16, v58
	v_and_b32_e32 v57, 0xffff0000, v58
	v_pk_mul_f32 v[146:147], v[192:193], v[146:147]
	v_add_f32_e32 v58, 1.0, v62
	v_lshlrev_b32_e32 v62, 16, v63
	v_rcp_f32_e32 v208, v58
	v_mul_f32_e32 v58, 0xbfb8aa3b, v62
	v_exp_f32_e32 v64, v58
	v_and_b32_e32 v58, 0xffff0000, v63
	v_mul_f32_e32 v63, 0xbfb8aa3b, v58
	v_exp_f32_e32 v63, v63
	v_pk_mul_f32 v[174:175], v[208:209], v[56:57]
	v_add_f32_e32 v56, 1.0, v64
	v_rcp_f32_e32 v210, v56
	v_add_f32_e32 v56, 1.0, v63
	v_pk_mul_f32 v[166:167], v[200:201], v[166:167]
	v_rcp_f32_e32 v168, v56
	v_mul_f32_e32 v56, v147, v147
	v_pk_mul_f32 v[60:61], v[202:203], v[60:61]
	v_fmac_f32_e32 v56, v167, v167
	v_fmac_f32_e32 v56, v61, v61
	v_pk_mul_f32 v[170:171], v[206:207], v[170:171]
	v_fmac_f32_e32 v56, v173, v173
	v_lshlrev_b32_e32 v63, 16, v59
	v_fmac_f32_e32 v56, v171, v171
	v_pk_mul_f32 v[62:63], v[210:211], v[62:63]
	v_and_b32_e32 v59, 0xffff0000, v59
	v_fmac_f32_e32 v56, v175, v175
	v_pk_mul_f32 v[168:169], v[168:169], v[58:59]
	v_fmac_f32_e32 v56, v63, v63
	v_fmac_f32_e32 v56, v169, v169
	v_ashrrev_i32_e32 v129, 31, v128
	s_nop 0
	v_add_f32_dpp v56, v56, v56 quad_perm:[1,0,3,2] row_mask:0xf bank_mask:0xf
	s_nop 1
	v_add_f32_dpp v56, v56, v56 quad_perm:[2,3,0,1] row_mask:0xf bank_mask:0xf
	s_nop 1
	v_add_f32_dpp v56, v56, v56 row_half_mirror row_mask:0xf bank_mask:0xf
	s_nop 1
	v_add_f32_dpp v56, v56, v56 row_mirror row_mask:0xf bank_mask:0xf
	ds_swizzle_b32 v57, v56 offset:swizzle(SWAP,16)
	s_waitcnt lgkmcnt(0)
	v_add_f32_e32 v56, v56, v57
	v_mov_b32_e32 v57, v56
	s_nop 1
	v_permlane32_swap_b32_e32 v56, v57
	v_add_f32_e32 v56, v56, v57
	v_fmamk_f32 v56, v56, 0x3b000000, v196
	v_mul_f32_e32 v57, 0x4b800000, v56
	v_cmp_gt_f32_e32 vcc, s35, v56
	s_nop 1
	v_cndmask_b32_e32 v56, v56, v57, vcc
	v_rsq_f32_e32 v56, v56
	s_nop 0
	v_mul_f32_e32 v57, 0x45800000, v56
	v_cndmask_b32_e32 v59, v56, v57, vcc
	v_mul_f32_e32 v56, v147, v59
	v_mul_f32_e32 v57, v167, v59
	v_mul_f32_e32 v56, v146, v56
	v_mul_f32_e32 v57, v166, v57
	v_cvt_pk_bf16_f32 v56, v56, v57
	v_mul_f32_e32 v57, v61, v59
	v_mul_f32_e32 v58, v173, v59
	v_mul_f32_e32 v57, v60, v57
	v_mul_f32_e32 v58, v172, v58
	v_cvt_pk_bf16_f32 v57, v57, v58
	v_mul_f32_e32 v58, v171, v59
	v_mul_f32_e32 v60, v175, v59
	v_mul_f32_e32 v58, v170, v58
	v_mul_f32_e32 v60, v174, v60
	v_cvt_pk_bf16_f32 v58, v58, v60
	v_mul_f32_e32 v60, v63, v59
	v_mul_f32_e32 v59, v169, v59
	v_mul_f32_e32 v60, v62, v60
	v_mul_f32_e32 v59, v168, v59
	v_cvt_pk_bf16_f32 v59, v60, v59
	v_lshl_add_u64 v[60:61], s[38:39], 0, v[128:129]
	v_lshlrev_b64 v[60:61], 11, v[60:61]
	v_lshl_add_u64 v[60:61], v[72:73], 0, v[60:61]
	global_store_dwordx4 v[60:61], v[56:59], off offset:1024
	s_waitcnt vmcnt(5)
	v_and_b32_e32 v184, 0xffff0000, v44
	v_lshlrev_b32_e32 v182, 16, v44
	v_mul_f32_e32 v44, 0xbfb8aa3b, v184
	v_exp_f32_e32 v44, v44
	v_mov_b32_e32 v142, v161
	v_pk_mul_f32 v[160:161], v[104:105], v[142:143]
	v_lshlrev_b32_e32 v183, 16, v40
	v_and_b32_e32 v185, 0xffff0000, v40
	v_add_f32_e32 v40, 1.0, v44
	v_lshlrev_b32_e32 v188, 16, v45
	v_add_f32_e32 v161, v160, v161
	v_rcp_f32_e32 v160, v40
	v_mul_f32_e32 v40, 0xbfb8aa3b, v188
	v_exp_f32_e32 v44, v40
	v_and_b32_e32 v40, 0xffff0000, v45
	v_mul_f32_e32 v45, 0xbfb8aa3b, v40
	v_lshlrev_b32_e32 v60, 16, v49
	v_and_b32_e32 v128, 0xffff0000, v49
	v_mul_f32_e32 v49, 0xbfb8aa3b, v182
	v_exp_f32_e32 v45, v45
	v_exp_f32_e32 v49, v49
	v_mov_b32_e32 v140, v159
	v_pk_mul_f32 v[166:167], v[98:99], v[140:141]
	v_mov_b32_e32 v138, v157
	v_add_f32_e32 v44, 1.0, v44
	v_mov_b32_e32 v144, v163
	v_add_f32_e32 v167, v166, v167
	v_pk_mul_f32 v[168:169], v[100:101], v[138:139]
	v_rcp_f32_e32 v166, v44
	v_add_f32_e32 v44, 1.0, v45
	v_pk_mul_f32 v[162:163], v[102:103], v[144:145]
	v_add_f32_e32 v169, v168, v169
	v_add_f32_e32 v49, 1.0, v49
	v_rcp_f32_e32 v168, v44
	v_lshlrev_b32_e32 v44, 16, v46
	v_and_b32_e32 v190, 0xffff0000, v46
	v_add_f32_e32 v163, v162, v163
	v_rcp_f32_e32 v162, v49
	v_mul_f32_e32 v49, 0xbfb8aa3b, v44
	v_mul_f32_e32 v46, 0xbfb8aa3b, v190
	v_exp_f32_e32 v49, v49
	v_exp_f32_e32 v46, v46
	v_mov_b32_e32 v136, v155
	v_mov_b32_e32 v134, v153
	v_pk_mul_f32 v[170:171], v[94:95], v[136:137]
	v_pk_mul_f32 v[172:173], v[96:97], v[134:135]
	v_lshlrev_b32_e32 v45, 16, v42
	v_add_f32_e32 v49, 1.0, v49
	v_and_b32_e32 v191, 0xffff0000, v42
	v_add_f32_e32 v42, 1.0, v46
	v_lshlrev_b32_e32 v192, 16, v47
	v_add_f32_e32 v171, v170, v171
	v_add_f32_e32 v173, v172, v173
	v_rcp_f32_e32 v170, v49
	v_rcp_f32_e32 v172, v42
	v_mul_f32_e32 v42, 0xbfb8aa3b, v192
	v_add_u32_e32 v49, 4, v124
	v_lshlrev_b32_e32 v56, 16, v48
	v_lshlrev_b32_e32 v58, 16, v52
	v_exp_f32_e32 v46, v42
	v_and_b32_e32 v42, 0xffff0000, v47
	v_cmp_gt_u32_e32 vcc, s46, v49
	s_waitcnt vmcnt(3)
	v_lshlrev_b32_e32 v59, 16, v36
	v_lshlrev_b32_e32 v57, 16, v32
	v_and_b32_e32 v48, 0xffff0000, v48
	v_and_b32_e32 v52, 0xffff0000, v52
	v_lshlrev_b32_e32 v62, 16, v53
	v_and_b32_e32 v146, 0xffff0000, v53
	v_mul_f32_e32 v47, 0xbfb8aa3b, v42
	v_cndmask_b32_e64 v67, 0, 1.0, vcc
	v_and_b32_e32 v53, 0xffff0000, v36
	v_and_b32_e32 v49, 0xffff0000, v32
	v_lshlrev_b32_e32 v61, 16, v33
	v_and_b32_e32 v129, 0xffff0000, v33
	v_pk_mul_f32 v[32:33], v[56:57], v[58:59]
	v_exp_f32_e32 v47, v47
	v_lshlrev_b32_e32 v63, 16, v37
	v_and_b32_e32 v147, 0xffff0000, v37
	v_pk_mul_f32 v[32:33], v[66:67], v[32:33]
	v_pk_mul_f32 v[36:37], v[48:49], v[52:53]
	v_fmac_f32_e32 v163, v12, v32
	v_pk_mul_f32 v[36:37], v[66:67], v[36:37]
	v_pk_mul_f32 v[48:49], v[60:61], v[62:63]
	v_lshlrev_b32_e32 v148, 16, v50
	v_lshlrev_b32_e32 v150, 16, v54
	v_lshlrev_b32_e32 v152, 16, v51
	v_and_b32_e32 v156, 0xffff0000, v51
	v_mov_b32_e32 v132, v151
	v_mov_b32_e32 v130, v149
	v_lshlrev_b32_e32 v151, 16, v38
	v_lshlrev_b32_e32 v149, 16, v34
	v_and_b32_e32 v51, 0xffff0000, v34
	v_lshlrev_b32_e32 v153, 16, v35
	v_and_b32_e32 v157, 0xffff0000, v35
	v_pk_mul_f32 v[34:35], v[162:163], v[182:183]
	v_fmac_f32_e32 v161, v13, v36
	v_pk_mul_f32 v[48:49], v[66:67], v[48:49]
	v_pk_mul_f32 v[56:57], v[128:129], v[146:147]
	v_and_b32_e32 v50, 0xffff0000, v50
	v_and_b32_e32 v54, 0xffff0000, v54
	v_lshlrev_b32_e32 v154, 16, v55
	v_and_b32_e32 v158, 0xffff0000, v55
	v_pk_mul_f32 v[174:175], v[90:91], v[132:133]
	v_lshlrev_b32_e32 v189, 16, v41
	v_add_f32_e32 v46, 1.0, v46
	v_and_b32_e32 v55, 0xffff0000, v38
	v_lshlrev_b32_e32 v155, 16, v39
	v_and_b32_e32 v159, 0xffff0000, v39
	v_pk_mul_f32 v[38:39], v[160:161], v[184:185]
	v_fmac_f32_e32 v167, v14, v48
	v_pk_mul_f32 v[56:57], v[66:67], v[56:57]
	v_pk_mul_f32 v[58:59], v[148:149], v[150:151]
	v_mul_f32_e32 v64, v35, v35
	v_add_f32_e32 v175, v174, v175
	v_pk_mul_f32 v[180:181], v[92:93], v[130:131]
	v_and_b32_e32 v41, 0xffff0000, v41
	v_rcp_f32_e32 v174, v46
	v_add_f32_e32 v46, 1.0, v47
	v_pk_mul_f32 v[52:53], v[166:167], v[188:189]
	v_fmac_f32_e32 v169, v15, v56
	v_pk_mul_f32 v[58:59], v[66:67], v[58:59]
	v_pk_mul_f32 v[50:51], v[50:51], v[54:55]
	v_fmac_f32_e32 v64, v39, v39
	v_add_f32_e32 v181, v180, v181
	v_rcp_f32_e32 v180, v46
	v_pk_mul_f32 v[40:41], v[168:169], v[40:41]
	v_fmac_f32_e32 v171, v4, v58
	v_pk_mul_f32 v[50:51], v[66:67], v[50:51]
	v_pk_mul_f32 v[60:61], v[152:153], v[154:155]
	v_fmac_f32_e32 v64, v53, v53
	v_pk_mul_f32 v[44:45], v[170:171], v[44:45]
	v_fmac_f32_e32 v173, v5, v50
	v_pk_mul_f32 v[60:61], v[66:67], v[60:61]
	v_pk_mul_f32 v[124:125], v[156:157], v[158:159]
	v_fmac_f32_e32 v64, v41, v41
	v_lshlrev_b32_e32 v193, 16, v43
	v_pk_mul_f32 v[54:55], v[172:173], v[190:191]
	v_fmac_f32_e32 v175, v6, v60
	v_pk_mul_f32 v[124:125], v[66:67], v[124:125]
	v_fmac_f32_e32 v64, v45, v45
	v_and_b32_e32 v43, 0xffff0000, v43
	v_pk_mul_f32 v[62:63], v[174:175], v[192:193]
	v_fmac_f32_e32 v181, v7, v124
	v_fmac_f32_e32 v64, v55, v55
	v_pk_mul_f32 v[42:43], v[180:181], v[42:43]
	v_fmac_f32_e32 v64, v63, v63
	v_fmac_f32_e32 v64, v43, v43
	v_pk_mul_f32 v[32:33], v[118:119], v[32:33]
	v_ashrrev_i32_e32 v127, 31, v126
	v_fma_f32 v32, v8, v145, v32
	v_lshl_add_u64 v[46:47], s[38:39], 0, v[126:127]
	v_add_f32_dpp v64, v64, v64 quad_perm:[1,0,3,2] row_mask:0xf bank_mask:0xf
	v_add_f32_e32 v127, v32, v33
	v_pk_mul_f32 v[32:33], v[120:121], v[36:37]
	v_lshlrev_b64 v[46:47], 11, v[46:47]
	v_fma_f32 v32, v9, v143, v32
	v_add_f32_dpp v36, v64, v64 quad_perm:[2,3,0,1] row_mask:0xf bank_mask:0xf
	v_add_f32_e32 v37, v32, v33
	v_pk_mul_f32 v[32:33], v[114:115], v[48:49]
	v_lshl_add_u64 v[46:47], v[72:73], 0, v[46:47]
	v_fma_f32 v32, v10, v141, v32
	v_add_f32_dpp v36, v36, v36 row_half_mirror row_mask:0xf bank_mask:0xf
	v_add_f32_e32 v49, v32, v33
	v_pk_mul_f32 v[32:33], v[116:117], v[56:57]
	v_add_f32_dpp v36, v36, v36 row_mirror row_mask:0xf bank_mask:0xf
	v_fma_f32 v32, v11, v139, v32
	ds_swizzle_b32 v48, v36 offset:swizzle(SWAP,16)
	v_add_f32_e32 v57, v32, v33
	v_pk_mul_f32 v[32:33], v[110:111], v[58:59]
	s_nop 0
	v_fma_f32 v32, v0, v137, v32
	v_add_f32_e32 v59, v32, v33
	v_pk_mul_f32 v[32:33], v[112:113], v[50:51]
	s_nop 0
	v_fma_f32 v32, v1, v135, v32
	v_add_f32_e32 v51, v32, v33
	s_waitcnt lgkmcnt(0)
	v_add_f32_e32 v32, v36, v48
	v_mov_b32_e32 v33, v32
	s_nop 1
	v_permlane32_swap_b32_e32 v32, v33
	v_add_f32_e32 v32, v32, v33
	v_fmamk_f32 v32, v32, 0x3b000000, v196
	v_mul_f32_e32 v33, 0x4b800000, v32
	v_cmp_gt_f32_e32 vcc, s35, v32
	s_nop 1
	v_cndmask_b32_e32 v32, v32, v33, vcc
	v_rsq_f32_e32 v36, v32
	v_pk_mul_f32 v[32:33], v[106:107], v[60:61]
	s_nop 0
	v_fma_f32 v32, v2, v133, v32
	v_add_f32_e32 v61, v32, v33
	v_mul_f32_e32 v32, 0x45800000, v36
	v_cndmask_b32_e32 v36, v36, v32, vcc
	v_mul_f32_e32 v32, v35, v36
	v_mul_f32_e32 v33, v39, v36
	v_mul_f32_e32 v32, v34, v32
	v_mul_f32_e32 v33, v38, v33
	v_cvt_pk_bf16_f32 v32, v32, v33
	v_mul_f32_e32 v33, v53, v36
	v_mul_f32_e32 v34, v41, v36
	v_mul_f32_e32 v33, v52, v33
	v_mul_f32_e32 v34, v40, v34
	v_cvt_pk_bf16_f32 v33, v33, v34
	v_mul_f32_e32 v34, v45, v36
	v_mul_f32_e32 v35, v55, v36
	v_mul_f32_e32 v34, v44, v34
	v_mul_f32_e32 v35, v54, v35
	v_cvt_pk_bf16_f32 v34, v34, v35
	v_mul_f32_e32 v35, v63, v36
	v_mul_f32_e32 v35, v62, v35
	v_mul_f32_e32 v36, v43, v36
	v_mul_f32_e32 v36, v42, v36
	v_cvt_pk_bf16_f32 v35, v35, v36
	global_store_dwordx4 v[46:47], v[32:35], off offset:1024
	s_nop 1
	v_pk_mul_f32 v[32:33], v[108:109], v[124:125]
	v_ashrrev_i32_e32 v123, 31, v122
	v_fma_f32 v35, v3, v131, v32
	s_waitcnt vmcnt(3)
	v_lshlrev_b32_e32 v32, 16, v28
	v_mul_f32_e32 v34, 0xbfb8aa3b, v32
	v_exp_f32_e32 v36, v34
	v_and_b32_e32 v34, 0xffff0000, v28
	v_mul_f32_e32 v28, 0xbfb8aa3b, v34
	v_exp_f32_e32 v28, v28
	v_add_f32_e32 v39, v35, v33
	v_add_f32_e32 v33, 1.0, v36
	v_rcp_f32_e32 v126, v33
	v_add_f32_e32 v28, 1.0, v28
	v_rcp_f32_e32 v36, v28
	v_lshlrev_b32_e32 v28, 16, v29
	v_lshlrev_b32_e32 v33, 16, v24
	v_and_b32_e32 v35, 0xffff0000, v24
	v_mul_f32_e32 v24, 0xbfb8aa3b, v28
	v_pk_mul_f32 v[34:35], v[36:37], v[34:35]
	v_exp_f32_e32 v36, v24
	v_and_b32_e32 v24, 0xffff0000, v29
	v_mul_f32_e32 v29, 0xbfb8aa3b, v24
	v_exp_f32_e32 v37, v29
	v_add_f32_e32 v36, 1.0, v36
	v_rcp_f32_e32 v48, v36
	v_lshlrev_b32_e32 v29, 16, v25
	v_add_f32_e32 v36, 1.0, v37
	v_rcp_f32_e32 v56, v36
	v_lshlrev_b32_e32 v36, 16, v30
	v_mul_f32_e32 v37, 0xbfb8aa3b, v36
	v_exp_f32_e32 v37, v37
	v_and_b32_e32 v25, 0xffff0000, v25
	v_pk_mul_f32 v[40:41], v[56:57], v[24:25]
	v_pk_mul_f32 v[32:33], v[126:127], v[32:33]
	v_add_f32_e32 v24, 1.0, v37
	v_rcp_f32_e32 v58, v24
	v_and_b32_e32 v24, 0xffff0000, v30
	v_mul_f32_e32 v25, 0xbfb8aa3b, v24
	v_exp_f32_e32 v30, v25
	v_lshlrev_b32_e32 v37, 16, v26
	v_and_b32_e32 v25, 0xffff0000, v26
	v_pk_mul_f32 v[28:29], v[48:49], v[28:29]
	v_add_f32_e32 v26, 1.0, v30
	v_lshlrev_b32_e32 v30, 16, v31
	v_rcp_f32_e32 v50, v26
	v_mul_f32_e32 v26, 0xbfb8aa3b, v30
	v_exp_f32_e32 v38, v26
	v_and_b32_e32 v26, 0xffff0000, v31
	v_mul_f32_e32 v31, 0xbfb8aa3b, v26
	v_exp_f32_e32 v31, v31
	v_pk_mul_f32 v[42:43], v[50:51], v[24:25]
	v_add_f32_e32 v24, 1.0, v38
	v_rcp_f32_e32 v60, v24
	v_add_f32_e32 v24, 1.0, v31
	v_rcp_f32_e32 v38, v24
	v_mul_f32_e32 v24, v33, v33
	v_fmac_f32_e32 v24, v35, v35
	v_fmac_f32_e32 v24, v29, v29
	v_pk_mul_f32 v[36:37], v[58:59], v[36:37]
	v_fmac_f32_e32 v24, v41, v41
	v_lshlrev_b32_e32 v31, 16, v27
	v_fmac_f32_e32 v24, v37, v37
	v_pk_mul_f32 v[30:31], v[60:61], v[30:31]
	v_and_b32_e32 v27, 0xffff0000, v27
	v_fmac_f32_e32 v24, v43, v43
	v_pk_mul_f32 v[38:39], v[38:39], v[26:27]
	v_fmac_f32_e32 v24, v31, v31
	v_fmac_f32_e32 v24, v39, v39
	s_nop 1
	v_add_f32_dpp v24, v24, v24 quad_perm:[1,0,3,2] row_mask:0xf bank_mask:0xf
	s_nop 1
	v_add_f32_dpp v24, v24, v24 quad_perm:[2,3,0,1] row_mask:0xf bank_mask:0xf
	s_nop 1
	v_add_f32_dpp v24, v24, v24 row_half_mirror row_mask:0xf bank_mask:0xf
	s_nop 1
	v_add_f32_dpp v24, v24, v24 row_mirror row_mask:0xf bank_mask:0xf
	ds_swizzle_b32 v25, v24 offset:swizzle(SWAP,16)
	s_waitcnt lgkmcnt(0)
	v_add_f32_e32 v24, v24, v25
	v_mov_b32_e32 v25, v24
	s_nop 1
	v_permlane32_swap_b32_e32 v24, v25
	v_add_f32_e32 v24, v24, v25
	v_fmamk_f32 v24, v24, 0x3b000000, v196
	v_mul_f32_e32 v25, 0x4b800000, v24
	v_cmp_gt_f32_e32 vcc, s35, v24
	s_nop 1
	v_cndmask_b32_e32 v24, v24, v25, vcc
	v_rsq_f32_e32 v24, v24
	s_nop 0
	v_mul_f32_e32 v25, 0x45800000, v24
	v_cndmask_b32_e32 v27, v24, v25, vcc
	v_mul_f32_e32 v24, v33, v27
	v_mul_f32_e32 v25, v35, v27
	v_mul_f32_e32 v24, v32, v24
	v_mul_f32_e32 v25, v34, v25
	v_cvt_pk_bf16_f32 v24, v24, v25
	v_mul_f32_e32 v25, v29, v27
	v_mul_f32_e32 v26, v41, v27
	v_mul_f32_e32 v25, v28, v25
	v_mul_f32_e32 v26, v40, v26
	v_cvt_pk_bf16_f32 v25, v25, v26
	v_mul_f32_e32 v26, v37, v27
	v_mul_f32_e32 v28, v43, v27
	v_mul_f32_e32 v26, v36, v26
	v_mul_f32_e32 v28, v42, v28
	v_cvt_pk_bf16_f32 v26, v26, v28
	v_mul_f32_e32 v28, v31, v27
	v_mul_f32_e32 v27, v39, v27
	v_mul_f32_e32 v28, v30, v28
	v_mul_f32_e32 v27, v38, v27
	v_cvt_pk_bf16_f32 v27, v28, v27
	v_lshl_add_u64 v[28:29], s[38:39], 0, v[122:123]
	v_lshlrev_b64 v[28:29], 11, v[28:29]
	v_lshl_add_u64 v[28:29], v[72:73], 0, v[28:29]
	global_store_dwordx4 v[28:29], v[24:27], off offset:1024
	s_and_b64 vcc, exec, s[0:1]
	s_mov_b64 s[0:1], 0
	s_cbranch_vccnz .LBB0_270
	s_bitcmp1_b32 s3, 3
	s_cbranch_scc0 .Lb_adv
	s_mov_b32 s98, 1
	s_branch .LBB0_255
